# NSA selected-block step: wave skips the whole tile (QK, bias, softmax) when none of its 32 queries selected that block
# baseline (speedup 1.0000x reference)
.Lsel_nn0:
	s_cmp_lt_i32 s17, 0
	s_cselect_b32 s24, s43, s17
	v_add_u32_e32 v6, s24, v136
	v_add_u32_e32 v2, s24, v137
	v_lshlrev_b32_e32 v6, 12, v6
	v_lshlrev_b32_e32 v2, 12, v2
	v_mov_b32_e32 v7, v1
	v_mov_b32_e32 v3, v1
	v_lshl_add_u64 v[6:7], v[122:123], 0, v[6:7]
	v_lshl_add_u64 v[2:3], v[124:125], 0, v[2:3]
	global_load_dwordx4 v[6:9], v[6:7], off offset:2816
	global_load_dwordx4 v[2:5], v[2:3], off offset:3584
	s_lshr_b32 s24, s43, 6
	v_lshrrev_b64 v[14:15], s24, v[120:121]
	v_and_b32_e32 v14, 1, v14
	v_cmp_eq_u32_e32 vcc, 1, v14
	s_cbranch_vccz .Lsel_skip0
	ds_read_b128 v[126:129], v161 offset:0
	ds_read_b128 v[130:133], v161 offset:4608
	ds_read_b128 v[164:167], v161 offset:32
	ds_read_b128 v[10:13], v161 offset:4640
	s_waitcnt lgkmcnt(3)
	v_mfma_f32_32x32x16_bf16 v[96:111], v[126:129], v[144:147], 0
	ds_read_b128 v[126:129], v161 offset:64
	s_waitcnt lgkmcnt(3)
	v_mfma_f32_32x32x16_bf16 v[80:95], v[130:133], v[144:147], 0
	ds_read_b128 v[130:133], v161 offset:4672
	s_waitcnt lgkmcnt(3)
	v_mfma_f32_32x32x16_bf16 v[96:111], v[164:167], v[148:151], v[96:111]
	ds_read_b128 v[164:167], v161 offset:96
	s_waitcnt lgkmcnt(3)
	v_mfma_f32_32x32x16_bf16 v[80:95], v[10:13], v[148:151], v[80:95]
	ds_read_b128 v[10:13], v161 offset:4704
	s_waitcnt lgkmcnt(3)
	v_mfma_f32_32x32x16_bf16 v[96:111], v[126:129], v[152:155], v[96:111]
	s_waitcnt lgkmcnt(2)
	v_mfma_f32_32x32x16_bf16 v[80:95], v[130:133], v[152:155], v[80:95]
	s_waitcnt lgkmcnt(1)
	v_mfma_f32_32x32x16_bf16 v[96:111], v[164:167], v[156:159], v[96:111]
	s_waitcnt lgkmcnt(0)
	v_mfma_f32_32x32x16_bf16 v[80:95], v[10:13], v[156:159], v[80:95]
	v_add_u32_e32 v163, s43, v139
	v_sub_u32_e32 v163, v163, v205
	v_cvt_f32_i32_e32 v163, v163
	v_mul_f32_e32 v0, v186, v163
	v_cndmask_b32_e32 v0, v225, v0, vcc
	s_nop 7
	v_fma_f32 v96, v96, s84, v0
	v_fmamk_f32 v15, v186, 0x3f800000, v0
	v_fma_f32 v97, v97, s84, v15
	v_fmamk_f32 v14, v186, 0x40000000, v0
	v_fma_f32 v98, v98, s84, v14
	v_fmamk_f32 v15, v186, 0x40400000, v0
	v_fma_f32 v99, v99, s84, v15
	v_fmamk_f32 v14, v186, 0x41000000, v0
	v_fma_f32 v100, v100, s84, v14
	v_fmamk_f32 v15, v186, 0x41100000, v0
	v_fma_f32 v101, v101, s84, v15
	v_fmamk_f32 v14, v186, 0x41200000, v0
	v_fma_f32 v102, v102, s84, v14
	v_fmamk_f32 v15, v186, 0x41300000, v0
	v_fma_f32 v103, v103, s84, v15
	v_fmamk_f32 v14, v186, 0x41800000, v0
	v_fma_f32 v104, v104, s84, v14
	v_fmamk_f32 v15, v186, 0x41880000, v0
	v_fma_f32 v105, v105, s84, v15
	v_fmamk_f32 v14, v186, 0x41900000, v0
	v_fma_f32 v106, v106, s84, v14
	v_fmamk_f32 v15, v186, 0x41980000, v0
	v_fma_f32 v107, v107, s84, v15
	v_fmamk_f32 v14, v186, 0x41c00000, v0
	v_fma_f32 v108, v108, s84, v14
	v_fmamk_f32 v15, v186, 0x41c80000, v0
	v_fma_f32 v109, v109, s84, v15
	v_fmamk_f32 v14, v186, 0x41d00000, v0
	v_fma_f32 v110, v110, s84, v14
	v_fmamk_f32 v15, v186, 0x41d80000, v0
	v_fma_f32 v111, v111, s84, v15
	v_fmamk_f32 v14, v186, 0x42000000, v0
	v_fma_f32 v80, v80, s84, v14
	v_fmamk_f32 v15, v186, 0x42040000, v0
	v_fma_f32 v81, v81, s84, v15
	v_fmamk_f32 v14, v186, 0x42080000, v0
	v_fma_f32 v82, v82, s84, v14
	v_fmamk_f32 v15, v186, 0x420c0000, v0
	v_fma_f32 v83, v83, s84, v15
	v_fmamk_f32 v14, v186, 0x42200000, v0
	v_fma_f32 v84, v84, s84, v14
	v_fmamk_f32 v15, v186, 0x42240000, v0
	v_fma_f32 v85, v85, s84, v15
	v_fmamk_f32 v14, v186, 0x42280000, v0
	v_fma_f32 v86, v86, s84, v14
	v_fmamk_f32 v15, v186, 0x422c0000, v0
	v_fma_f32 v87, v87, s84, v15
	v_fmamk_f32 v14, v186, 0x42400000, v0
	v_fma_f32 v88, v88, s84, v14
	v_fmamk_f32 v15, v186, 0x42440000, v0
	v_fma_f32 v89, v89, s84, v15
	v_fmamk_f32 v14, v186, 0x42480000, v0
	v_fma_f32 v90, v90, s84, v14
	v_fmamk_f32 v15, v186, 0x424c0000, v0
	v_fma_f32 v91, v91, s84, v15
	v_fmamk_f32 v14, v186, 0x42600000, v0
	v_fma_f32 v92, v92, s84, v14
	v_fmamk_f32 v15, v186, 0x42640000, v0
	v_fma_f32 v93, v93, s84, v15
	v_fmamk_f32 v14, v186, 0x42680000, v0
	v_fma_f32 v94, v94, s84, v14
	v_fmamk_f32 v15, v186, 0x426c0000, v0
	v_fma_f32 v95, v95, s84, v15
	s_add_i32 s24, s43, 63
	s_cmp_gt_i32 s24, s52
	s_cbranch_scc1 .Lsel_mask0

.Lsel_nn1:
	s_cmp_lt_i32 s17, 0
	s_cselect_b32 s24, s43, s17
	v_add_u32_e32 v116, s24, v136
	v_add_u32_e32 v112, s24, v137
	v_lshlrev_b32_e32 v116, 12, v116
	v_lshlrev_b32_e32 v112, 12, v112
	v_mov_b32_e32 v117, v1
	v_mov_b32_e32 v113, v1
	v_lshl_add_u64 v[116:117], v[122:123], 0, v[116:117]
	v_lshl_add_u64 v[112:113], v[124:125], 0, v[112:113]
	global_load_dwordx4 v[116:119], v[116:117], off offset:2816
	global_load_dwordx4 v[112:115], v[112:113], off offset:3584
	s_lshr_b32 s24, s43, 6
	v_lshrrev_b64 v[14:15], s24, v[120:121]
	v_and_b32_e32 v14, 1, v14
	v_cmp_eq_u32_e32 vcc, 1, v14
	s_cbranch_vccz .Lsel_skip1
	ds_read_b128 v[126:129], v161 offset:13312
	ds_read_b128 v[130:133], v161 offset:17920
	ds_read_b128 v[164:167], v161 offset:13344
	ds_read_b128 v[10:13], v161 offset:17952
	s_waitcnt lgkmcnt(3)
	v_mfma_f32_32x32x16_bf16 v[96:111], v[126:129], v[144:147], 0
	ds_read_b128 v[126:129], v161 offset:13376
	s_waitcnt lgkmcnt(3)
	v_mfma_f32_32x32x16_bf16 v[80:95], v[130:133], v[144:147], 0
	ds_read_b128 v[130:133], v161 offset:17984
	s_waitcnt lgkmcnt(3)
	v_mfma_f32_32x32x16_bf16 v[96:111], v[164:167], v[148:151], v[96:111]
	ds_read_b128 v[164:167], v161 offset:13408
	s_waitcnt lgkmcnt(3)
	v_mfma_f32_32x32x16_bf16 v[80:95], v[10:13], v[148:151], v[80:95]
	ds_read_b128 v[10:13], v161 offset:18016
	s_waitcnt lgkmcnt(3)
	v_mfma_f32_32x32x16_bf16 v[96:111], v[126:129], v[152:155], v[96:111]
	s_waitcnt lgkmcnt(2)
	v_mfma_f32_32x32x16_bf16 v[80:95], v[130:133], v[152:155], v[80:95]
	s_waitcnt lgkmcnt(1)
	v_mfma_f32_32x32x16_bf16 v[96:111], v[164:167], v[156:159], v[96:111]
	s_waitcnt lgkmcnt(0)
	v_mfma_f32_32x32x16_bf16 v[80:95], v[10:13], v[156:159], v[80:95]
	v_add_u32_e32 v163, s43, v139
	v_sub_u32_e32 v163, v163, v205
	v_cvt_f32_i32_e32 v163, v163
	v_mul_f32_e32 v0, v186, v163
	v_cndmask_b32_e32 v0, v225, v0, vcc
	s_nop 7
	v_fma_f32 v96, v96, s84, v0
	v_fmamk_f32 v15, v186, 0x3f800000, v0
	v_fma_f32 v97, v97, s84, v15
	v_fmamk_f32 v14, v186, 0x40000000, v0
	v_fma_f32 v98, v98, s84, v14
	v_fmamk_f32 v15, v186, 0x40400000, v0
	v_fma_f32 v99, v99, s84, v15
	v_fmamk_f32 v14, v186, 0x41000000, v0
	v_fma_f32 v100, v100, s84, v14
	v_fmamk_f32 v15, v186, 0x41100000, v0
	v_fma_f32 v101, v101, s84, v15
	v_fmamk_f32 v14, v186, 0x41200000, v0
	v_fma_f32 v102, v102, s84, v14
	v_fmamk_f32 v15, v186, 0x41300000, v0
	v_fma_f32 v103, v103, s84, v15
	v_fmamk_f32 v14, v186, 0x41800000, v0
	v_fma_f32 v104, v104, s84, v14
	v_fmamk_f32 v15, v186, 0x41880000, v0
	v_fma_f32 v105, v105, s84, v15
	v_fmamk_f32 v14, v186, 0x41900000, v0
	v_fma_f32 v106, v106, s84, v14
	v_fmamk_f32 v15, v186, 0x41980000, v0
	v_fma_f32 v107, v107, s84, v15
	v_fmamk_f32 v14, v186, 0x41c00000, v0
	v_fma_f32 v108, v108, s84, v14
	v_fmamk_f32 v15, v186, 0x41c80000, v0
	v_fma_f32 v109, v109, s84, v15
	v_fmamk_f32 v14, v186, 0x41d00000, v0
	v_fma_f32 v110, v110, s84, v14
	v_fmamk_f32 v15, v186, 0x41d80000, v0
	v_fma_f32 v111, v111, s84, v15
	v_fmamk_f32 v14, v186, 0x42000000, v0
	v_fma_f32 v80, v80, s84, v14
	v_fmamk_f32 v15, v186, 0x42040000, v0
	v_fma_f32 v81, v81, s84, v15
	v_fmamk_f32 v14, v186, 0x42080000, v0
	v_fma_f32 v82, v82, s84, v14
	v_fmamk_f32 v15, v186, 0x420c0000, v0
	v_fma_f32 v83, v83, s84, v15
	v_fmamk_f32 v14, v186, 0x42200000, v0
	v_fma_f32 v84, v84, s84, v14
	v_fmamk_f32 v15, v186, 0x42240000, v0
	v_fma_f32 v85, v85, s84, v15
	v_fmamk_f32 v14, v186, 0x42280000, v0
	v_fma_f32 v86, v86, s84, v14
	v_fmamk_f32 v15, v186, 0x422c0000, v0
	v_fma_f32 v87, v87, s84, v15
	v_fmamk_f32 v14, v186, 0x42400000, v0
	v_fma_f32 v88, v88, s84, v14
	v_fmamk_f32 v15, v186, 0x42440000, v0
	v_fma_f32 v89, v89, s84, v15
	v_fmamk_f32 v14, v186, 0x42480000, v0
	v_fma_f32 v90, v90, s84, v14
	v_fmamk_f32 v15, v186, 0x424c0000, v0
	v_fma_f32 v91, v91, s84, v15
	v_fmamk_f32 v14, v186, 0x42600000, v0
	v_fma_f32 v92, v92, s84, v14
	v_fmamk_f32 v15, v186, 0x42640000, v0
	v_fma_f32 v93, v93, s84, v15
	v_fmamk_f32 v14, v186, 0x42680000, v0
	v_fma_f32 v94, v94, s84, v14
	v_fmamk_f32 v15, v186, 0x426c0000, v0
	v_fma_f32 v95, v95, s84, v15
	s_add_i32 s24, s43, 63
	s_cmp_gt_i32 s24, s52
	s_cbranch_scc1 .Lsel_mask1
